# grid barrier: all waiters poll the global arrival counter (>= round*nXCD) directly; release-flag hop no longer on the critical path
# baseline (speedup 1.0000x reference)
.LBB0_1043:
	s_or_b64 exec, exec, s[2:3]
	s_waitcnt vmcnt(0)
	v_readfirstlane_b32 s2, v1
	v_readlane_b32 s3, v255, 10
	s_nop 0
	v_add3_u32 v0, s2, v0, 1
	v_readlane_b32 s2, v255, 6
	s_mul_i32 s2, s3, s2
	s_nop 0
	v_cmp_ne_u32_e32 vcc, s2, v0
	s_and_saveexec_b64 s[2:3], vcc
	s_xor_b64 s[2:3], exec, s[2:3]
	s_cbranch_execz .LBB0_1047
	v_readlane_b32 s4, v254, 21
	v_readlane_b32 s5, v254, 22
	v_readlane_b32 s6, v255, 10
	v_readlane_b32 s99, v254, 61
	s_mul_i32 s6, s6, s99
	s_nop 3
	global_load_dword v0, v193, s[4:5] sc1
	s_waitcnt vmcnt(0)
	v_cmp_le_u32_e32 vcc, s6, v0
	s_cbranch_vccnz .LBB0_1046

.LBB0_1050:
	s_or_b64 exec, exec, s[4:5]
	s_waitcnt vmcnt(0)
	v_readfirstlane_b32 s2, v1
	v_readlane_b32 s8, v255, 10
	s_nop 0
	v_add3_u32 v0, s2, v0, 1
	v_readlane_b32 s2, v254, 61
	s_mul_i32 s2, s8, s2
	s_nop 0
	v_cmp_ne_u32_e32 vcc, s2, v0
	s_and_saveexec_b64 s[2:3], vcc
	v_readlane_b32 s6, v254, 23
	s_xor_b64 s[2:3], exec, s[2:3]
	v_readlane_b32 s7, v254, 24
	s_cbranch_execz .LBB0_1053
	v_readlane_b32 s6, v254, 21
	v_readlane_b32 s7, v254, 22
	v_readlane_b32 s99, v254, 61
	s_mul_i32 s98, s8, s99
	s_nop 3
	global_load_dword v0, v193, s[6:7] sc1
	s_waitcnt vmcnt(0)
	v_cmp_le_u32_e32 vcc, s98, v0
	s_cbranch_vccnz .LBB0_1053
.LBB0_1052:
	s_sleep 1
	global_load_dword v0, v193, s[6:7] sc1
	s_waitcnt vmcnt(0)
	v_cmp_gt_u32_e32 vcc, s98, v0
	s_cbranch_vccnz .LBB0_1052
